# grid barrier: the XCD leaders no longer post the per-XCD release word (nobody polls it any more), so their closing wait only covers the cache invalidate
# speedup vs baseline: 1.0046x; 1.0046x over previous
.LBB0_104:
	s_or_b64 exec, exec, s[12:13]
	s_mov_b64 s[12:13], exec
	v_mbcnt_lo_u32_b32 v0, s12, 0
	v_mbcnt_hi_u32_b32 v0, s13, v0
	v_cmp_eq_u32_e32 vcc, 0, v0
	s_waitcnt vmcnt(0)
	buffer_inv sc1
	s_and_saveexec_b64 s[14:15], vcc
	s_cbranch_execz .LBB0_106
	s_bcnt1_i32_b64 s3, s[12:13]
	v_mov_b32_e32 v0, 0x2000
	v_mov_b32_e32 v1, s3
.LBB0_106:
	s_or_b64 exec, exec, s[14:15]
	s_waitcnt vmcnt(0)

.LBB0_160:
	s_or_b64 exec, exec, s[10:11]
	s_mov_b64 s[10:11], exec
	v_mbcnt_lo_u32_b32 v0, s10, 0
	v_mbcnt_hi_u32_b32 v0, s11, v0
	v_cmp_eq_u32_e32 vcc, 0, v0
	s_waitcnt vmcnt(0)
	buffer_inv sc1
	s_and_saveexec_b64 s[12:13], vcc
	s_cbranch_execz .LBB0_162
	s_bcnt1_i32_b64 s3, s[10:11]
	v_mov_b32_e32 v0, 0x2000
	v_mov_b32_e32 v1, s3
.LBB0_162:
	s_or_b64 exec, exec, s[12:13]
	s_waitcnt vmcnt(0)

.LBB0_432:
	s_or_b64 exec, exec, s[10:11]
	s_mov_b64 s[10:11], exec
	v_mbcnt_lo_u32_b32 v0, s10, 0
	v_mbcnt_hi_u32_b32 v0, s11, v0
	v_cmp_eq_u32_e32 vcc, 0, v0
	s_waitcnt vmcnt(0)
	buffer_inv sc1
	s_and_saveexec_b64 s[12:13], vcc
	s_cbranch_execz .LBB0_434
	s_bcnt1_i32_b64 s3, s[10:11]
	v_mov_b32_e32 v0, 0x2000
	v_mov_b32_e32 v1, s3
.LBB0_434:
	s_or_b64 exec, exec, s[12:13]
	s_waitcnt vmcnt(0)

.LBB0_490:
	s_or_b64 exec, exec, s[8:9]
	s_mov_b64 s[8:9], exec
	v_mbcnt_lo_u32_b32 v0, s8, 0
	v_mbcnt_hi_u32_b32 v0, s9, v0
	v_cmp_eq_u32_e32 vcc, 0, v0
	s_waitcnt vmcnt(0)
	buffer_inv sc1
	s_and_saveexec_b64 s[10:11], vcc
	s_cbranch_execz .LBB0_492
	s_bcnt1_i32_b64 s3, s[8:9]
	v_mov_b32_e32 v0, 0x2000
	v_mov_b32_e32 v1, s3
.LBB0_492:
	s_or_b64 exec, exec, s[10:11]
	s_waitcnt vmcnt(0)

.LBB0_687:
	s_or_b64 exec, exec, s[8:9]
	s_mov_b64 s[8:9], exec
	v_mbcnt_lo_u32_b32 v0, s8, 0
	v_mbcnt_hi_u32_b32 v0, s9, v0
	v_cmp_eq_u32_e32 vcc, 0, v0
	s_waitcnt vmcnt(0)
	buffer_inv sc1
	s_and_saveexec_b64 s[10:11], vcc
	s_cbranch_execz .LBB0_689
	s_bcnt1_i32_b64 s3, s[8:9]
	v_mov_b32_e32 v0, 0x2000
	v_mov_b32_e32 v1, s3
.LBB0_689:
	s_or_b64 exec, exec, s[10:11]
	s_waitcnt vmcnt(0)

.LBB0_911:
	s_or_b64 exec, exec, s[8:9]
	s_mov_b64 s[8:9], exec
	v_mbcnt_lo_u32_b32 v0, s8, 0
	v_mbcnt_hi_u32_b32 v0, s9, v0
	v_cmp_eq_u32_e32 vcc, 0, v0
	s_waitcnt vmcnt(0)
	buffer_inv sc1
	s_and_saveexec_b64 s[10:11], vcc
	s_cbranch_execz .LBB0_913
	s_bcnt1_i32_b64 s3, s[8:9]
	v_mov_b32_e32 v0, 0x2000
	v_mov_b32_e32 v1, s3
.LBB0_913:
	s_or_b64 exec, exec, s[10:11]
	s_waitcnt vmcnt(0)

.LBB0_966:
	s_or_b64 exec, exec, s[8:9]
	s_mov_b64 s[8:9], exec
	v_mbcnt_lo_u32_b32 v0, s8, 0
	v_mbcnt_hi_u32_b32 v0, s9, v0
	v_cmp_eq_u32_e32 vcc, 0, v0
	s_waitcnt vmcnt(0)
	buffer_inv sc1
	s_and_saveexec_b64 s[10:11], vcc
	s_cbranch_execz .LBB0_968
	s_bcnt1_i32_b64 s3, s[8:9]
	v_mov_b32_e32 v0, 0x2000
	v_mov_b32_e32 v1, s3
.LBB0_968:
	s_or_b64 exec, exec, s[10:11]
	s_waitcnt vmcnt(0)

.LBB0_1123:
	s_or_b64 exec, exec, s[8:9]
	s_mov_b64 s[8:9], exec
	v_mbcnt_lo_u32_b32 v0, s8, 0
	v_mbcnt_hi_u32_b32 v0, s9, v0
	v_cmp_eq_u32_e32 vcc, 0, v0
	s_waitcnt vmcnt(0)
	buffer_inv sc1
	s_and_saveexec_b64 s[10:11], vcc
	s_cbranch_execz .LBB0_1125
	s_bcnt1_i32_b64 s3, s[8:9]
	v_mov_b32_e32 v0, 0x2000
	v_mov_b32_e32 v1, s3
.LBB0_1125:
	s_or_b64 exec, exec, s[10:11]
	s_waitcnt vmcnt(0)

.LBB0_1199:
	s_or_b64 exec, exec, s[10:11]
	s_mov_b64 s[10:11], exec
	v_mbcnt_lo_u32_b32 v0, s10, 0
	v_mbcnt_hi_u32_b32 v0, s11, v0
	v_cmp_eq_u32_e32 vcc, 0, v0
	s_waitcnt vmcnt(0)
	buffer_inv sc1
	s_and_saveexec_b64 s[14:15], vcc
	s_cbranch_execz .LBB0_1201
	s_bcnt1_i32_b64 s3, s[10:11]
	v_mov_b32_e32 v0, 0x2000
	v_mov_b32_e32 v1, s3
.LBB0_1201:
	s_or_b64 exec, exec, s[14:15]
	s_waitcnt vmcnt(0)

.LBB0_1299:
	s_or_b64 exec, exec, s[10:11]
	s_mov_b64 s[10:11], exec
	v_mbcnt_lo_u32_b32 v0, s10, 0
	v_mbcnt_hi_u32_b32 v0, s11, v0
	v_cmp_eq_u32_e32 vcc, 0, v0
	s_waitcnt vmcnt(0)
	buffer_inv sc1
	s_and_saveexec_b64 s[14:15], vcc
	s_cbranch_execz .LBB0_1301
	s_bcnt1_i32_b64 s3, s[10:11]
	v_mov_b32_e32 v0, 0x2000
	v_mov_b32_e32 v1, s3
.LBB0_1301:
	s_or_b64 exec, exec, s[14:15]
	s_waitcnt vmcnt(0)

.LBB0_1424:
	s_or_b64 exec, exec, s[12:13]
	s_mov_b64 s[12:13], exec
	v_mbcnt_lo_u32_b32 v0, s12, 0
	v_mbcnt_hi_u32_b32 v0, s13, v0
	v_cmp_eq_u32_e32 vcc, 0, v0
	s_waitcnt vmcnt(0)
	buffer_inv sc1
	s_and_saveexec_b64 s[14:15], vcc
	s_cbranch_execz .LBB0_1426
	s_bcnt1_i32_b64 s3, s[12:13]
	v_mov_b32_e32 v0, 0x2000
	v_mov_b32_e32 v1, s3
.LBB0_1426:
	s_or_b64 exec, exec, s[14:15]
	s_waitcnt vmcnt(0)

.LBB0_1538:
	s_or_b64 exec, exec, s[12:13]
	s_mov_b64 s[12:13], exec
	v_mbcnt_lo_u32_b32 v0, s12, 0
	v_mbcnt_hi_u32_b32 v0, s13, v0
	v_cmp_eq_u32_e32 vcc, 0, v0
	s_waitcnt vmcnt(0)
	buffer_inv sc1
	s_and_saveexec_b64 s[14:15], vcc
	s_cbranch_execz .LBB0_1540
	s_bcnt1_i32_b64 s3, s[12:13]
	v_mov_b32_e32 v0, 0x2000
	v_mov_b32_e32 v1, s3
.LBB0_1540:
	s_or_b64 exec, exec, s[14:15]
	s_waitcnt vmcnt(0)
